# conv row-major path: tile-row LDS reads of each output step issued together
# speedup vs baseline: 1.0053x; 1.0053x over previous
; #define LAS __attribute__((address_space(3)))
; __device__ __forceinline__ void st8(bf16_t* p, f32x4 a, f32x4 b) { u32x4 w; w.x = pk2(a[0], a[1]); w.y = pk2(a[2], a[3]); w.z = pk2(b[0], b[1]); w.w = pk2(b[2], b[3]); *(u32x4*)p = w; }
; __device__ __forceinline__ float silu(float x) { return x * __builtin_amdgcn_rcpf(1.f + __builtin_amdgcn_exp2f(-1.4426950408889634f * x)); }
; __device__ __forceinline__ void ph_conv(LAS unsigned char* lds) {
;     ...
;             for (int q = 0; q < 16; ++q) { const int l = q * 8 + lr;
;                 f32x4 a0 = b0, a1 = b1;
; #pragma unroll
;                 for (int k = 0; k < 4; ++k) { const u32x4 uw = *(const LAS u32x4*)(tile + (l + k) * 128 + cgp * 16);
;                     const f32x4 x0 = {bflo(uw.x), bfhi(uw.x), bflo(uw.y), bfhi(uw.y)}, x1 = {bflo(uw.z), bfhi(uw.z), bflo(uw.w), bfhi(uw.w)};
;                     a0 += wa[k] * x0; a1 += wb[k] * x1; }
; #pragma unroll
;                 for (int e = 0; e < 4; ++e) { a0[e] = silu(a0[e]); a1[e] = silu(a1[e]); }
;                 st8(dst + (unsigned)(l * 128 + cgp * 8), a0, a1); }
.LBB0_738:
	ds_read_b128 v[144:147], v0
	ds_read_b128 v[148:151], v0 offset:128
	ds_read_b128 v[152:155], v0 offset:256
	ds_read_b128 v[156:159], v0 offset:384
	s_waitcnt lgkmcnt(0)
	v_lshlrev_b32_e32 v50, 16, v144
	v_and_b32_e32 v51, 0xffff0000, v144
	v_lshlrev_b32_e32 v46, 16, v145
	v_and_b32_e32 v47, 0xffff0000, v145
	v_lshlrev_b32_e32 v52, 16, v146
	v_and_b32_e32 v53, 0xffff0000, v146
	v_lshlrev_b32_e32 v48, 16, v147
	v_and_b32_e32 v49, 0xffff0000, v147
	v_pk_fma_f32 v[54:55], v[8:9], v[46:47], v[40:41]
	v_pk_fma_f32 v[56:57], v[4:5], v[48:49], v[36:37]
	v_pk_fma_f32 v[50:51], v[6:7], v[50:51], v[38:39]
	v_pk_fma_f32 v[52:53], v[2:3], v[52:53], v[34:35]
	v_lshlrev_b32_e32 v58, 16, v148
	v_and_b32_e32 v59, 0xffff0000, v148
	v_lshlrev_b32_e32 v46, 16, v149
	v_and_b32_e32 v47, 0xffff0000, v149
	v_lshlrev_b32_e32 v60, 16, v150
	v_and_b32_e32 v61, 0xffff0000, v150
	v_lshlrev_b32_e32 v48, 16, v151
	v_and_b32_e32 v49, 0xffff0000, v151
	v_pk_fma_f32 v[54:55], v[12:13], v[46:47], v[54:55]
	v_pk_fma_f32 v[56:57], v[16:17], v[48:49], v[56:57]
	v_pk_fma_f32 v[50:51], v[10:11], v[58:59], v[50:51]
	v_pk_fma_f32 v[52:53], v[14:15], v[60:61], v[52:53]
	v_lshlrev_b32_e32 v58, 16, v152
	v_and_b32_e32 v59, 0xffff0000, v152
	v_lshlrev_b32_e32 v46, 16, v153
	v_and_b32_e32 v47, 0xffff0000, v153
	v_lshlrev_b32_e32 v60, 16, v154
	v_and_b32_e32 v61, 0xffff0000, v154
	v_lshlrev_b32_e32 v48, 16, v155
	v_and_b32_e32 v49, 0xffff0000, v155
	v_pk_fma_f32 v[54:55], v[20:21], v[46:47], v[54:55]
	v_pk_fma_f32 v[56:57], v[24:25], v[48:49], v[56:57]
	v_pk_fma_f32 v[52:53], v[22:23], v[60:61], v[52:53]
	v_pk_fma_f32 v[50:51], v[18:19], v[58:59], v[50:51]
	v_lshlrev_b32_e32 v60, 16, v158
	v_and_b32_e32 v61, 0xffff0000, v158
	v_lshlrev_b32_e32 v58, 16, v156
	v_and_b32_e32 v59, 0xffff0000, v156
	v_lshlrev_b32_e32 v46, 16, v157
	v_and_b32_e32 v47, 0xffff0000, v157
	v_pk_fma_f32 v[52:53], v[30:31], v[60:61], v[52:53]
	v_pk_fma_f32 v[46:47], v[28:29], v[46:47], v[54:55]
	v_mul_f32_e32 v55, 0xbfb8aa3b, v52
	v_exp_f32_e32 v55, v55
	v_lshlrev_b32_e32 v48, 16, v159
	v_and_b32_e32 v49, 0xffff0000, v159
	v_pk_fma_f32 v[50:51], v[26:27], v[58:59], v[50:51]
	v_add_f32_e32 v55, 1.0, v55
	v_pk_fma_f32 v[48:49], v[32:33], v[48:49], v[56:57]
	v_mul_f32_e32 v54, 0xbfb8aa3b, v50
	v_rcp_f32_e32 v56, v55
	v_mul_f32_e32 v55, 0xbfb8aa3b, v51
	v_exp_f32_e32 v54, v54
	v_exp_f32_e32 v55, v55
	v_lshl_add_u64 v[58:59], v[44:45], 0, s[42:43]
	v_add_f32_e32 v54, 1.0, v54
	v_add_f32_e32 v55, 1.0, v55
	v_rcp_f32_e32 v54, v54
	v_rcp_f32_e32 v55, v55
	s_nop 0
	v_pk_mul_f32 v[50:51], v[50:51], v[54:55]
	v_mul_f32_e32 v54, 0xbfb8aa3b, v53
	v_exp_f32_e32 v54, v54
	v_mul_f32_e32 v55, 0xbfb8aa3b, v48
	v_exp_f32_e32 v55, v55
	v_add_f32_e32 v54, 1.0, v54
	v_rcp_f32_e32 v57, v54
	v_add_f32_e32 v55, 1.0, v55
	v_mul_f32_e32 v54, 0xbfb8aa3b, v46
	v_exp_f32_e32 v54, v54
	v_pk_mul_f32 v[52:53], v[52:53], v[56:57]
	v_rcp_f32_e32 v56, v55
	v_mul_f32_e32 v55, 0xbfb8aa3b, v47
	v_exp_f32_e32 v55, v55
	v_add_f32_e32 v54, 1.0, v54
	v_rcp_f32_e32 v54, v54
	v_add_f32_e32 v55, 1.0, v55
	v_rcp_f32_e32 v55, v55
	s_nop 0
	v_pk_mul_f32 v[54:55], v[46:47], v[54:55]
	v_mul_f32_e32 v46, 0xbfb8aa3b, v49
	v_exp_f32_e32 v46, v46
	v_cvt_pk_bf16_f32 v47, v54, v55
	v_add_f32_e32 v46, 1.0, v46
	v_rcp_f32_e32 v57, v46
	v_cvt_pk_bf16_f32 v46, v50, v51
	v_pk_mul_f32 v[56:57], v[48:49], v[56:57]
	v_cvt_pk_bf16_f32 v48, v52, v53
	v_cvt_pk_bf16_f32 v49, v56, v57
	global_store_dwordx4 v[58:59], v[46:49], off
	ds_read_b128 v[160:163], v0 offset:1024
	ds_read_b128 v[164:167], v0 offset:1152
	ds_read_b128 v[168:171], v0 offset:1280
	ds_read_b128 v[172:175], v0 offset:1408
	s_waitcnt lgkmcnt(0)
; #define LAS __attribute__((address_space(3)))
; __device__ __forceinline__ void st8(bf16_t* p, f32x4 a, f32x4 b) { u32x4 w; w.x = pk2(a[0], a[1]); w.y = pk2(a[2], a[3]); w.z = pk2(b[0], b[1]); w.w = pk2(b[2], b[3]); *(u32x4*)p = w; }
; __device__ __forceinline__ float silu(float x) { return x * __builtin_amdgcn_rcpf(1.f + __builtin_amdgcn_exp2f(-1.4426950408889634f * x)); }
; __device__ __forceinline__ void ph_conv(LAS unsigned char* lds) {
;     ...
;             for (int q = 0; q < 16; ++q) { const int l = q * 8 + lr;
;                 f32x4 a0 = b0, a1 = b1;
; #pragma unroll
;                 for (int k = 0; k < 4; ++k) { const u32x4 uw = *(const LAS u32x4*)(tile + (l + k) * 128 + cgp * 16);
;                     const f32x4 x0 = {bflo(uw.x), bfhi(uw.x), bflo(uw.y), bfhi(uw.y)}, x1 = {bflo(uw.z), bfhi(uw.z), bflo(uw.w), bfhi(uw.w)};
;                     a0 += wa[k] * x0; a1 += wb[k] * x1; }
; #pragma unroll
;                 for (int e = 0; e < 4; ++e) { a0[e] = silu(a0[e]); a1[e] = silu(a1[e]); }
;                 st8(dst + (unsigned)(l * 128 + cgp * 8), a0, a1); }
	v_lshlrev_b32_e32 v50, 16, v160
	v_and_b32_e32 v51, 0xffff0000, v160
	v_lshlrev_b32_e32 v46, 16, v161
	v_and_b32_e32 v47, 0xffff0000, v161
	v_lshlrev_b32_e32 v52, 16, v162
	v_and_b32_e32 v53, 0xffff0000, v162
	v_lshlrev_b32_e32 v48, 16, v163
	v_and_b32_e32 v49, 0xffff0000, v163
	v_pk_fma_f32 v[54:55], v[8:9], v[46:47], v[40:41]
	v_pk_fma_f32 v[56:57], v[4:5], v[48:49], v[36:37]
	v_pk_fma_f32 v[50:51], v[6:7], v[50:51], v[38:39]
	v_pk_fma_f32 v[52:53], v[2:3], v[52:53], v[34:35]
	v_lshlrev_b32_e32 v58, 16, v164
	v_and_b32_e32 v59, 0xffff0000, v164
	v_lshlrev_b32_e32 v46, 16, v165
	v_and_b32_e32 v47, 0xffff0000, v165
	v_lshlrev_b32_e32 v60, 16, v166
	v_and_b32_e32 v61, 0xffff0000, v166
	v_lshlrev_b32_e32 v48, 16, v167
	v_and_b32_e32 v49, 0xffff0000, v167
	v_pk_fma_f32 v[54:55], v[12:13], v[46:47], v[54:55]
	v_pk_fma_f32 v[56:57], v[16:17], v[48:49], v[56:57]
	v_pk_fma_f32 v[50:51], v[10:11], v[58:59], v[50:51]
	v_pk_fma_f32 v[52:53], v[14:15], v[60:61], v[52:53]
	v_lshlrev_b32_e32 v58, 16, v168
	v_and_b32_e32 v59, 0xffff0000, v168
	v_lshlrev_b32_e32 v46, 16, v169
	v_and_b32_e32 v47, 0xffff0000, v169
	v_lshlrev_b32_e32 v60, 16, v170
	v_and_b32_e32 v61, 0xffff0000, v170
	v_lshlrev_b32_e32 v48, 16, v171
	v_and_b32_e32 v49, 0xffff0000, v171
	v_pk_fma_f32 v[54:55], v[20:21], v[46:47], v[54:55]
	v_pk_fma_f32 v[56:57], v[24:25], v[48:49], v[56:57]
	v_pk_fma_f32 v[52:53], v[22:23], v[60:61], v[52:53]
	v_pk_fma_f32 v[50:51], v[18:19], v[58:59], v[50:51]
	v_add_u32_e32 v0, 0x800, v0
	v_lshlrev_b32_e32 v60, 16, v174
	v_and_b32_e32 v61, 0xffff0000, v174
	v_lshlrev_b32_e32 v58, 16, v172
	v_and_b32_e32 v59, 0xffff0000, v172
	v_lshlrev_b32_e32 v46, 16, v173
	v_and_b32_e32 v47, 0xffff0000, v173
	v_pk_fma_f32 v[52:53], v[30:31], v[60:61], v[52:53]
	v_pk_fma_f32 v[46:47], v[28:29], v[46:47], v[54:55]
	v_mul_f32_e32 v55, 0xbfb8aa3b, v52
	v_exp_f32_e32 v55, v55
	v_lshlrev_b32_e32 v48, 16, v175
	v_and_b32_e32 v49, 0xffff0000, v175
	v_pk_fma_f32 v[50:51], v[26:27], v[58:59], v[50:51]
	v_add_f32_e32 v55, 1.0, v55
	v_pk_fma_f32 v[48:49], v[32:33], v[48:49], v[56:57]
	v_mul_f32_e32 v54, 0xbfb8aa3b, v50
	v_rcp_f32_e32 v56, v55
	v_mul_f32_e32 v55, 0xbfb8aa3b, v51
	v_exp_f32_e32 v54, v54
	v_exp_f32_e32 v55, v55
	v_lshl_add_u64 v[58:59], v[42:43], 0, s[42:43]
	s_add_u32 s42, s42, 0x1000
	v_add_f32_e32 v54, 1.0, v54
	v_add_f32_e32 v55, 1.0, v55
	v_rcp_f32_e32 v54, v54
	v_rcp_f32_e32 v55, v55
	s_addc_u32 s43, s43, 0
	s_cmpk_lg_u32 s42, 0x8000
	v_pk_mul_f32 v[50:51], v[50:51], v[54:55]
	v_mul_f32_e32 v54, 0xbfb8aa3b, v53
	v_exp_f32_e32 v54, v54
	v_mul_f32_e32 v55, 0xbfb8aa3b, v48
	v_exp_f32_e32 v55, v55
	v_add_f32_e32 v54, 1.0, v54
	v_rcp_f32_e32 v57, v54
	v_add_f32_e32 v55, 1.0, v55
	v_mul_f32_e32 v54, 0xbfb8aa3b, v46
	v_exp_f32_e32 v54, v54
	v_pk_mul_f32 v[52:53], v[52:53], v[56:57]
	v_rcp_f32_e32 v56, v55
	v_mul_f32_e32 v55, 0xbfb8aa3b, v47
	v_exp_f32_e32 v55, v55
	v_add_f32_e32 v54, 1.0, v54
	v_rcp_f32_e32 v54, v54
	v_add_f32_e32 v55, 1.0, v55
	v_rcp_f32_e32 v55, v55
	s_nop 0
	v_pk_mul_f32 v[54:55], v[46:47], v[54:55]
	v_mul_f32_e32 v46, 0xbfb8aa3b, v49
	v_exp_f32_e32 v46, v46
	v_cvt_pk_bf16_f32 v47, v54, v55
	v_add_f32_e32 v46, 1.0, v46
	v_rcp_f32_e32 v57, v46
	v_cvt_pk_bf16_f32 v46, v50, v51
	v_pk_mul_f32 v[56:57], v[48:49], v[56:57]
	v_cvt_pk_bf16_f32 v48, v52, v53
	v_cvt_pk_bf16_f32 v49, v56, v57
	global_store_dwordx4 v[58:59], v[46:49], off
	s_cbranch_scc1 .LBB0_738
	s_branch .LBB0_724
